# v019 + nt on out-proj epilogue x loads (cache-policy hints: P1 x loads, Gin proj stores, out-proj x loads, P5 y stores)
# baseline (speedup 1.0000x reference)
.LBB0_668:
	s_and_b64 vcc, exec, s[6:7]
	s_cbranch_vccz .LBB0_686
	s_ashr_i32 s3, s90, 3
	s_mul_hi_i32 s7, s3, 0x3000
	s_mulk_i32 s3, 0x3000
	v_readlane_b32 s36, v254, 50
	v_readlane_b32 s37, v254, 51
	s_add_u32 s6, s36, s3
	s_addc_u32 s7, s37, s7
	v_lshlrev_b64 v[132:133], 2, v[2:3]
	v_readlane_b32 s68, v254, 16
	s_waitcnt lgkmcnt(0)
	v_lshl_add_u64 v[134:135], s[6:7], 0, v[132:133]
	v_readlane_b32 s69, v254, 17
	v_lshl_add_u64 v[148:149], v[134:135], 0, s[54:55]
	v_add_co_u32_e32 v134, vcc, 0x2000, v134
	v_lshl_add_u64 v[212:213], s[68:69], 0, v[132:133]
	v_lshlrev_b64 v[132:133], 12, v[210:211]
	v_addc_co_u32_e32 v135, vcc, 0, v135, vcc
	v_lshl_add_u64 v[132:133], v[212:213], 0, v[132:133]
	global_load_dwordx4 v[232:235], v[132:133], off offset:16 nt
	global_load_dwordx4 v[140:143], v[148:149], off offset:16
	global_load_dwordx4 v[136:139], v[148:149], off offset:512
	global_load_dwordx4 v[236:239], v[132:133], off offset:512 nt
	global_load_dwordx4 v[144:147], v[134:135], off
	global_load_dwordx4 v[240:243], v[132:133], off nt
	global_load_dwordx4 v[244:247], v[132:133], off offset:528 nt
	s_nop 0
	global_load_dwordx4 v[132:135], v[148:149], off offset:528
	v_or_b32_e32 v218, 16, v210
	v_or_b32_e32 v216, 32, v210
	v_or_b32_e32 v214, 48, v210
	v_ashrrev_i32_e32 v219, 31, v218
	v_ashrrev_i32_e32 v217, 31, v216
	v_ashrrev_i32_e32 v215, 31, v214
	v_lshlrev_b64 v[148:149], 12, v[218:219]
	v_lshlrev_b64 v[150:151], 12, v[216:217]
	v_lshlrev_b64 v[152:153], 12, v[214:215]
	v_lshl_add_u64 v[148:149], v[212:213], 0, v[148:149]
	v_lshl_add_u64 v[150:151], v[212:213], 0, v[150:151]
	v_lshl_add_u64 v[152:153], v[212:213], 0, v[152:153]
	global_load_dwordx4 v[188:191], v[148:149], off offset:16 nt
	global_load_dwordx4 v[192:195], v[148:149], off nt
	global_load_dwordx4 v[180:183], v[148:149], off offset:528 nt
	global_load_dwordx4 v[184:187], v[148:149], off offset:512 nt
	global_load_dwordx4 v[172:175], v[150:151], off offset:16 nt
	global_load_dwordx4 v[176:179], v[150:151], off nt
	global_load_dwordx4 v[164:167], v[150:151], off offset:528 nt
	global_load_dwordx4 v[168:171], v[150:151], off offset:512 nt
	global_load_dwordx4 v[156:159], v[152:153], off offset:16 nt
	global_load_dwordx4 v[160:163], v[152:153], off nt
	s_nop 0
	global_load_dwordx4 v[148:151], v[152:153], off offset:528 nt
	s_nop 0
	global_load_dwordx4 v[152:155], v[152:153], off offset:512 nt
	v_readlane_b32 s38, v254, 52
	v_readlane_b32 s39, v254, 53
	v_readlane_b32 s70, v254, 18
	v_readlane_b32 s71, v254, 19
	v_readlane_b32 s72, v254, 20
	v_readlane_b32 s73, v254, 21
	v_readlane_b32 s74, v254, 22
	v_readlane_b32 s75, v254, 23
	v_readlane_b32 s76, v254, 24
	v_readlane_b32 s77, v254, 25
	v_readlane_b32 s78, v254, 26
	v_readlane_b32 s79, v254, 27
	v_readlane_b32 s80, v254, 28
	v_readlane_b32 s81, v254, 29
	v_readlane_b32 s82, v254, 30
	v_readlane_b32 s83, v254, 31
	s_waitcnt vmcnt(0)
	v_pk_fma_f32 v[248:249], v[10:11], v[142:143], v[234:235]
	v_pk_fma_f32 v[232:233], v[8:9], v[140:141], v[232:233]
	v_mul_f32_e32 v231, v249, v249
	v_cvt_pk_bf16_f32 v235, v248, v249
	v_pk_fma_f32 v[242:243], v[6:7], v[146:147], v[242:243]
	v_pk_fma_f32 v[240:241], v[4:5], v[144:145], v[240:241]
	v_mul_f32_e32 v252, v243, v243
	v_mul_f32_e32 v249, v241, v241
	v_mul_f32_e32 v1, v233, v233
	v_fmac_f32_e32 v249, v240, v240
	v_fmac_f32_e32 v252, v242, v242
	v_pk_fma_f32 v[236:237], v[36:37], v[136:137], v[236:237]
	v_cvt_pk_bf16_f32 v234, v232, v233
	v_fmac_f32_e32 v1, v232, v232
	v_cvt_pk_bf16_f32 v232, v240, v241
	v_add_f32_e32 v240, v249, v252
	v_pk_fma_f32 v[238:239], v[38:39], v[138:139], v[238:239]
	v_mul_f32_e32 v250, v237, v237
	v_fmac_f32_e32 v231, v248, v248
	v_add_f32_e32 v1, v240, v1
	v_pk_fma_f32 v[244:245], v[40:41], v[132:133], v[244:245]
	v_mul_f32_e32 v251, v239, v239
	v_fmac_f32_e32 v250, v236, v236
	v_add_f32_e32 v1, v231, v1
	v_pk_fma_f32 v[246:247], v[42:43], v[134:135], v[246:247]
	v_fmac_f32_e32 v251, v238, v238
	v_mul_f32_e32 v248, v245, v245
	v_add_f32_e32 v1, v250, v1
	v_mul_f32_e32 v253, v247, v247
	v_fmac_f32_e32 v248, v244, v244
	v_add_f32_e32 v1, v251, v1
	v_fmac_f32_e32 v253, v246, v246
	v_add_f32_e32 v1, v248, v1
	v_add_f32_e32 v1, v253, v1
	ds_bpermute_b32 v231, v226, v1
	v_lshlrev_b64 v[240:241], 11, v[210:211]
	v_lshl_add_u64 v[240:241], s[40:41], 0, v[240:241]
	v_cvt_pk_bf16_f32 v233, v242, v243
	v_lshl_add_u64 v[240:241], v[2:3], 1, v[240:241]
	s_waitcnt lgkmcnt(0)
	v_add_f32_e32 v1, v1, v231
	ds_bpermute_b32 v231, v227, v1
	global_store_dwordx4 v[240:241], v[232:235], off
	s_nop 1
	v_cvt_pk_bf16_f32 v232, v236, v237
	v_cvt_pk_bf16_f32 v233, v238, v239
	v_cvt_pk_bf16_f32 v234, v244, v245
	v_cvt_pk_bf16_f32 v235, v246, v247
	global_store_dwordx4 v[240:241], v[232:235], off offset:256
	s_and_saveexec_b64 s[6:7], s[8:9]
	s_cbranch_execz .LBB0_671
	s_lshl_b32 s34, s66, 2
	v_lshlrev_b64 v[232:233], 6, v[210:211]
	s_ashr_i32 s35, s34, 31
	v_lshl_add_u64 v[232:233], s[18:19], 0, v[232:233]
	v_lshl_add_u64 v[232:233], s[34:35], 2, v[232:233]
	s_lshl_b32 s14, s42, 2
	s_waitcnt lgkmcnt(0)
	v_add_f32_e32 v1, v1, v231
	v_lshl_add_u64 v[232:233], v[232:233], 0, s[14:15]
	global_store_dword v[232:233], v1, off

.LBB0_677:
	s_or_b64 exec, exec, s[6:7]
	v_add_u32_e32 v218, 0x80, v210
	v_ashrrev_i32_e32 v219, 31, v218
	s_waitcnt lgkmcnt(0)
	v_lshlrev_b64 v[148:149], 12, v[218:219]
	v_lshl_add_u64 v[148:149], v[212:213], 0, v[148:149]
	global_load_dwordx4 v[232:235], v[148:149], off nt
	global_load_dwordx4 v[236:239], v[148:149], off offset:16 nt
	global_load_dwordx4 v[240:243], v[148:149], off offset:512 nt
	global_load_dwordx4 v[244:247], v[148:149], off offset:528 nt
	v_add_u32_e32 v216, 0x90, v210
	v_add_u32_e32 v214, 0xa0, v210
	v_add_u32_e32 v210, 0xb0, v210
	v_ashrrev_i32_e32 v217, 31, v216
	v_ashrrev_i32_e32 v215, 31, v214
	v_ashrrev_i32_e32 v211, 31, v210
	v_lshlrev_b64 v[148:149], 12, v[216:217]
	v_lshlrev_b64 v[150:151], 12, v[214:215]
	v_lshlrev_b64 v[152:153], 12, v[210:211]
	v_lshl_add_u64 v[148:149], v[212:213], 0, v[148:149]
	v_lshl_add_u64 v[150:151], v[212:213], 0, v[150:151]
	v_lshl_add_u64 v[152:153], v[212:213], 0, v[152:153]
	global_load_dwordx4 v[188:191], v[148:149], off offset:16 nt
	global_load_dwordx4 v[192:195], v[148:149], off nt
	global_load_dwordx4 v[180:183], v[148:149], off offset:528 nt
	global_load_dwordx4 v[184:187], v[148:149], off offset:512 nt
	global_load_dwordx4 v[172:175], v[150:151], off offset:16 nt
	global_load_dwordx4 v[176:179], v[150:151], off nt
	global_load_dwordx4 v[164:167], v[150:151], off offset:528 nt
	global_load_dwordx4 v[168:171], v[150:151], off offset:512 nt
	global_load_dwordx4 v[156:159], v[152:153], off offset:16 nt
	global_load_dwordx4 v[160:163], v[152:153], off nt
	s_nop 0
	global_load_dwordx4 v[148:151], v[152:153], off offset:528 nt
	s_nop 0
	global_load_dwordx4 v[152:155], v[152:153], off offset:512 nt
	s_waitcnt vmcnt(15)
	v_pk_fma_f32 v[212:213], v[70:71], v[146:147], v[234:235]
	v_pk_fma_f32 v[248:249], v[68:69], v[144:145], v[232:233]
	s_waitcnt vmcnt(14)
	v_pk_fma_f32 v[236:237], v[72:73], v[140:141], v[236:237]
	v_mul_f32_e32 v1, v249, v249
	v_mul_f32_e32 v231, v213, v213
	v_pk_fma_f32 v[238:239], v[74:75], v[142:143], v[238:239]
	v_mul_f32_e32 v250, v237, v237
	v_fmac_f32_e32 v1, v248, v248
	v_fmac_f32_e32 v231, v212, v212
	s_waitcnt vmcnt(13)
	v_pk_fma_f32 v[240:241], v[100:101], v[136:137], v[240:241]
	v_mul_f32_e32 v251, v239, v239
	v_fmac_f32_e32 v250, v236, v236
	v_add_f32_e32 v1, v1, v231
	v_pk_fma_f32 v[242:243], v[102:103], v[138:139], v[242:243]
	v_mul_f32_e32 v252, v241, v241
	v_fmac_f32_e32 v251, v238, v238
	v_add_f32_e32 v1, v1, v250
	s_waitcnt vmcnt(12)
	v_pk_fma_f32 v[244:245], v[104:105], v[132:133], v[244:245]
	v_mul_f32_e32 v253, v243, v243
	v_fmac_f32_e32 v252, v240, v240
	v_add_f32_e32 v1, v251, v1
	v_pk_fma_f32 v[246:247], v[106:107], v[134:135], v[246:247]
	v_mul_f32_e32 v222, v245, v245
	v_fmac_f32_e32 v253, v242, v242
	v_add_f32_e32 v1, v252, v1
	v_mul_f32_e32 v196, v247, v247
	v_fmac_f32_e32 v222, v244, v244
	v_add_f32_e32 v1, v253, v1
	v_fmac_f32_e32 v196, v246, v246
	v_add_f32_e32 v1, v222, v1
	v_add_f32_e32 v1, v196, v1
	ds_bpermute_b32 v196, v226, v1
	v_cvt_pk_bf16_f32 v233, v212, v213
	v_lshlrev_b64 v[212:213], 11, v[218:219]
	v_lshl_add_u64 v[212:213], s[40:41], 0, v[212:213]
	v_cvt_pk_bf16_f32 v234, v236, v237
	s_waitcnt lgkmcnt(0)
	v_add_f32_e32 v1, v1, v196
	v_lshl_add_u64 v[236:237], v[2:3], 1, v[212:213]
	ds_bpermute_b32 v212, v227, v1
	v_cvt_pk_bf16_f32 v232, v248, v249
	v_cvt_pk_bf16_f32 v235, v238, v239
	global_store_dwordx4 v[236:237], v[232:235], off
	s_nop 1
	v_cvt_pk_bf16_f32 v232, v240, v241
	v_cvt_pk_bf16_f32 v233, v242, v243
	v_cvt_pk_bf16_f32 v234, v244, v245
	v_cvt_pk_bf16_f32 v235, v246, v247
	global_store_dwordx4 v[236:237], v[232:235], off offset:256
	s_and_saveexec_b64 s[6:7], s[8:9]
	s_cbranch_execz .LBB0_679
	s_waitcnt lgkmcnt(0)
	v_add_f32_e32 v1, v1, v212
	s_lshl_b32 s34, s66, 2
	v_lshlrev_b64 v[212:213], 6, v[218:219]
	s_ashr_i32 s35, s34, 31
	v_lshl_add_u64 v[212:213], s[18:19], 0, v[212:213]
	v_lshl_add_u64 v[212:213], s[34:35], 2, v[212:213]
	s_lshl_b32 s14, s42, 2
	v_lshl_add_u64 v[212:213], v[212:213], 0, s[14:15]
	global_store_dword v[212:213], v1, off
